# adds: removed the compiler's vmcnt(0) store drain in front of the next panel's row-statistics preload (gate/up and input-projection GEMMs)
# baseline (speedup 1.0000x reference)
; __device__ __forceinline__ void rstd_unit_start(RstdState& st, const float* ssq, int pm, int tid) {
;     if (pm != st.last_pm && tid < 256) st.pre = *(const f32x4*)(ssq + (size_t)(pm * BM + tid) * 4);
; }
.LBB0_152:
	s_cmp_lg_u32 s12, s56
	s_cselect_b64 s[6:7], -1, 0
	s_and_b64 s[14:15], s[38:39], s[6:7]
	s_and_saveexec_b64 s[6:7], s[14:15]
	s_cbranch_execz .LBB0_154
	s_nop 0
	v_lshl_add_u32 v0, s12, 8, v154
	v_ashrrev_i32_e32 v1, 31, v0
	v_lshl_add_u64 v[0:1], v[0:1], 4, s[88:89]
	global_load_dwordx4 v[0:3], v[0:1], off

; #define LAS __attribute__((address_space(3)))
; __device__ __forceinline__ unsigned pk2(float lo, float hi) { f32x2 v = {lo, hi}; bf16x2_t b = __builtin_convertvector(v, bf16x2_t); return __builtin_bit_cast(unsigned, b); }
; __device__ __forceinline__ float silu_f(float g) { return g * __builtin_amdgcn_rcpf(1.f + __builtin_amdgcn_exp2f(g * -1.4426950408889634f)); }
;     __device__ __forceinline__ void operator()(const f32x4 (&acc)[2][2][4][2], const Unit& u, int wr, int wc, int fr, int fq, LAS unsigned char* lds, int tid, State& st) const {
;         const int row0 = u.pm * BM + wr * 64 + fr, col0 = u.pn * 128 + wc * 32 + 8 * fq;
;         const LAS float* RT = rstd_panel(st, lds, u.pm, tid);
; #pragma unroll
;         for (int ai = 0; ai < 2; ++ai) {
;             float rs[4];
; #pragma unroll
;             for (int m = 0; m < 4; ++m) rs[m] = RT[wr * 64 + fr + ai * HALF + m * 16];
; #pragma unroll
;             for (int m = 0; m < 4; ++m) {
;                 const int row = row0 + ai * HALF + m * 16; const float r = rs[m];
;                 const f32x4 g0 = acc[ai][0][m][0] * r, g1 = acc[ai][0][m][1] * r, u0 = acc[ai][1][m][0] * r, u1 = acc[ai][1][m][1] * r;
;                 u32x4 w;
;                 w.x = pk2(silu_f(g0[0]) * u0[0], silu_f(g0[1]) * u0[1]); w.y = pk2(silu_f(g0[2]) * u0[2], silu_f(g0[3]) * u0[3]);
;                 w.z = pk2(silu_f(g1[0]) * u1[0], silu_f(g1[1]) * u1[1]); w.w = pk2(silu_f(g1[2]) * u1[2], silu_f(g1[3]) * u1[3]);
;                 *(u32x4*)(H + (size_t)row * DFF + col0) = w;
;             }
.LBB0_725:
	ds_read2_b32 v[154:155], v150 offset1:16
	ds_read2_b32 v[142:143], v150 offset0:32 offset1:48
	ds_read2_b32 v[156:157], v150 offset0:128 offset1:144
	ds_read2_b32 v[144:145], v150 offset0:160 offset1:176
	s_andn2_b64 vcc, exec, s[42:43]
	v_lshl_or_b32 v216, s21, 7, v151
	v_lshl_add_u32 v217, s9, 8, v147
	v_mov_b32_e32 v204, 1.0
	v_mul_u32_u24_e32 v214, 0x1600, v217
	v_lshl_add_u32 v214, v216, 1, v214
	s_waitcnt lgkmcnt(0)
	v_mul_f32_e32 v200, 0xbfb8aa3b, v154
	v_mul_f32_e32 v202, v154, v154
	v_mov_b32_e32 v215, v214
	v_pk_mul_f32 v[206:207], v[128:129], v[200:201] op_sel_hi:[1,0]
	v_pk_mul_f32 v[208:209], v[130:131], v[200:201] op_sel_hi:[1,0]
	v_pk_mul_f32 v[210:211], v[124:125], v[200:201] op_sel_hi:[1,0]
	v_pk_mul_f32 v[212:213], v[126:127], v[200:201] op_sel_hi:[1,0]
	v_exp_f32_e32 v206, v206
	v_exp_f32_e32 v207, v207
	v_exp_f32_e32 v208, v208
	v_exp_f32_e32 v209, v209
	v_exp_f32_e32 v210, v210
	v_exp_f32_e32 v211, v211
	v_exp_f32_e32 v212, v212
	v_exp_f32_e32 v213, v213
	v_pk_mul_f32 v[120:121], v[128:129], v[120:121]
	v_pk_mul_f32 v[122:123], v[130:131], v[122:123]
	v_pk_mul_f32 v[116:117], v[124:125], v[116:117]
	v_pk_mul_f32 v[118:119], v[126:127], v[118:119]
	v_pk_add_f32 v[206:207], v[206:207], v[204:205] op_sel_hi:[1,0]
	v_pk_add_f32 v[208:209], v[208:209], v[204:205] op_sel_hi:[1,0]
	v_pk_add_f32 v[210:211], v[210:211], v[204:205] op_sel_hi:[1,0]
	v_pk_add_f32 v[212:213], v[212:213], v[204:205] op_sel_hi:[1,0]
	v_rcp_f32_e32 v206, v206
	v_rcp_f32_e32 v207, v207
	v_rcp_f32_e32 v208, v208
	v_rcp_f32_e32 v209, v209
	v_rcp_f32_e32 v210, v210
	v_rcp_f32_e32 v211, v211
	v_rcp_f32_e32 v212, v212
	v_rcp_f32_e32 v213, v213
	v_pk_mul_f32 v[120:121], v[120:121], v[202:203] op_sel_hi:[1,0]
	v_pk_mul_f32 v[122:123], v[122:123], v[202:203] op_sel_hi:[1,0]
	v_pk_mul_f32 v[116:117], v[116:117], v[202:203] op_sel_hi:[1,0]
	v_pk_mul_f32 v[118:119], v[118:119], v[202:203] op_sel_hi:[1,0]
	v_pk_mul_f32 v[120:121], v[120:121], v[206:207]
	v_pk_mul_f32 v[122:123], v[122:123], v[208:209]
	v_pk_mul_f32 v[116:117], v[116:117], v[210:211]
	v_pk_mul_f32 v[118:119], v[118:119], v[212:213]
	v_cvt_pk_bf16_f32 v120, v120, v121
	v_cvt_pk_bf16_f32 v121, v122, v123
	v_cvt_pk_bf16_f32 v122, v116, v117
	v_cvt_pk_bf16_f32 v123, v118, v119
	global_store_dwordx4 v215, v[120:123], s[94:95]
	v_mul_f32_e32 v200, 0xbfb8aa3b, v155
	v_mul_f32_e32 v202, v155, v155
	v_add_u32_e32 v215, 0x16000, v214
	v_pk_mul_f32 v[206:207], v[112:113], v[200:201] op_sel_hi:[1,0]
	v_pk_mul_f32 v[208:209], v[114:115], v[200:201] op_sel_hi:[1,0]
	v_pk_mul_f32 v[210:211], v[108:109], v[200:201] op_sel_hi:[1,0]
	v_pk_mul_f32 v[212:213], v[110:111], v[200:201] op_sel_hi:[1,0]
	v_exp_f32_e32 v206, v206
	v_exp_f32_e32 v207, v207
	v_exp_f32_e32 v208, v208
	v_exp_f32_e32 v209, v209
	v_exp_f32_e32 v210, v210
	v_exp_f32_e32 v211, v211
	v_exp_f32_e32 v212, v212
	v_exp_f32_e32 v213, v213
	v_pk_mul_f32 v[104:105], v[112:113], v[104:105]
	v_pk_mul_f32 v[106:107], v[114:115], v[106:107]
	v_pk_mul_f32 v[100:101], v[108:109], v[100:101]
	v_pk_mul_f32 v[102:103], v[110:111], v[102:103]
	v_pk_add_f32 v[206:207], v[206:207], v[204:205] op_sel_hi:[1,0]
	v_pk_add_f32 v[208:209], v[208:209], v[204:205] op_sel_hi:[1,0]
	v_pk_add_f32 v[210:211], v[210:211], v[204:205] op_sel_hi:[1,0]
	v_pk_add_f32 v[212:213], v[212:213], v[204:205] op_sel_hi:[1,0]
	v_rcp_f32_e32 v206, v206
	v_rcp_f32_e32 v207, v207
	v_rcp_f32_e32 v208, v208
	v_rcp_f32_e32 v209, v209
	v_rcp_f32_e32 v210, v210
	v_rcp_f32_e32 v211, v211
	v_rcp_f32_e32 v212, v212
	v_rcp_f32_e32 v213, v213
	v_pk_mul_f32 v[104:105], v[104:105], v[202:203] op_sel_hi:[1,0]
	v_pk_mul_f32 v[106:107], v[106:107], v[202:203] op_sel_hi:[1,0]
	v_pk_mul_f32 v[100:101], v[100:101], v[202:203] op_sel_hi:[1,0]
	v_pk_mul_f32 v[102:103], v[102:103], v[202:203] op_sel_hi:[1,0]
	v_pk_mul_f32 v[104:105], v[104:105], v[206:207]
	v_pk_mul_f32 v[106:107], v[106:107], v[208:209]
	v_pk_mul_f32 v[100:101], v[100:101], v[210:211]
	v_pk_mul_f32 v[102:103], v[102:103], v[212:213]
	v_cvt_pk_bf16_f32 v104, v104, v105
	v_cvt_pk_bf16_f32 v105, v106, v107
	v_cvt_pk_bf16_f32 v106, v100, v101
	v_cvt_pk_bf16_f32 v107, v102, v103
	global_store_dwordx4 v215, v[104:107], s[94:95]
	v_mul_f32_e32 v200, 0xbfb8aa3b, v142
	v_mul_f32_e32 v202, v142, v142
	v_add_u32_e32 v215, 0x2c000, v214
	v_pk_mul_f32 v[206:207], v[96:97], v[200:201] op_sel_hi:[1,0]
	v_pk_mul_f32 v[208:209], v[98:99], v[200:201] op_sel_hi:[1,0]
	v_pk_mul_f32 v[210:211], v[92:93], v[200:201] op_sel_hi:[1,0]
	v_pk_mul_f32 v[212:213], v[94:95], v[200:201] op_sel_hi:[1,0]
	v_exp_f32_e32 v206, v206
	v_exp_f32_e32 v207, v207
	v_exp_f32_e32 v208, v208
	v_exp_f32_e32 v209, v209
	v_exp_f32_e32 v210, v210
	v_exp_f32_e32 v211, v211
	v_exp_f32_e32 v212, v212
	v_exp_f32_e32 v213, v213
	v_pk_mul_f32 v[88:89], v[96:97], v[88:89]
	v_pk_mul_f32 v[90:91], v[98:99], v[90:91]
	v_pk_mul_f32 v[84:85], v[92:93], v[84:85]
	v_pk_mul_f32 v[86:87], v[94:95], v[86:87]
	v_pk_add_f32 v[206:207], v[206:207], v[204:205] op_sel_hi:[1,0]
	v_pk_add_f32 v[208:209], v[208:209], v[204:205] op_sel_hi:[1,0]
	v_pk_add_f32 v[210:211], v[210:211], v[204:205] op_sel_hi:[1,0]
	v_pk_add_f32 v[212:213], v[212:213], v[204:205] op_sel_hi:[1,0]
	v_rcp_f32_e32 v206, v206
	v_rcp_f32_e32 v207, v207
	v_rcp_f32_e32 v208, v208
	v_rcp_f32_e32 v209, v209
	v_rcp_f32_e32 v210, v210
	v_rcp_f32_e32 v211, v211
	v_rcp_f32_e32 v212, v212
	v_rcp_f32_e32 v213, v213
	v_pk_mul_f32 v[88:89], v[88:89], v[202:203] op_sel_hi:[1,0]
	v_pk_mul_f32 v[90:91], v[90:91], v[202:203] op_sel_hi:[1,0]
	v_pk_mul_f32 v[84:85], v[84:85], v[202:203] op_sel_hi:[1,0]
	v_pk_mul_f32 v[86:87], v[86:87], v[202:203] op_sel_hi:[1,0]
; #define LAS __attribute__((address_space(3)))
; __device__ __forceinline__ unsigned pk2(float lo, float hi) { f32x2 v = {lo, hi}; bf16x2_t b = __builtin_convertvector(v, bf16x2_t); return __builtin_bit_cast(unsigned, b); }
; __device__ __forceinline__ float silu_f(float g) { return g * __builtin_amdgcn_rcpf(1.f + __builtin_amdgcn_exp2f(g * -1.4426950408889634f)); }
;     __device__ __forceinline__ void operator()(const f32x4 (&acc)[2][2][4][2], const Unit& u, int wr, int wc, int fr, int fq, LAS unsigned char* lds, int tid, State& st) const {
;         const int row0 = u.pm * BM + wr * 64 + fr, col0 = u.pn * 128 + wc * 32 + 8 * fq;
;         const LAS float* RT = rstd_panel(st, lds, u.pm, tid);
; #pragma unroll
;         for (int ai = 0; ai < 2; ++ai) {
;             float rs[4];
; #pragma unroll
;             for (int m = 0; m < 4; ++m) rs[m] = RT[wr * 64 + fr + ai * HALF + m * 16];
; #pragma unroll
;             for (int m = 0; m < 4; ++m) {
;                 const int row = row0 + ai * HALF + m * 16; const float r = rs[m];
;                 const f32x4 g0 = acc[ai][0][m][0] * r, g1 = acc[ai][0][m][1] * r, u0 = acc[ai][1][m][0] * r, u1 = acc[ai][1][m][1] * r;
;                 u32x4 w;
;                 w.x = pk2(silu_f(g0[0]) * u0[0], silu_f(g0[1]) * u0[1]); w.y = pk2(silu_f(g0[2]) * u0[2], silu_f(g0[3]) * u0[3]);
;                 w.z = pk2(silu_f(g1[0]) * u1[0], silu_f(g1[1]) * u1[1]); w.w = pk2(silu_f(g1[2]) * u1[2], silu_f(g1[3]) * u1[3]);
;                 *(u32x4*)(H + (size_t)row * DFF + col0) = w;
;             }
	v_pk_mul_f32 v[88:89], v[88:89], v[206:207]
	v_pk_mul_f32 v[90:91], v[90:91], v[208:209]
	v_pk_mul_f32 v[84:85], v[84:85], v[210:211]
	v_pk_mul_f32 v[86:87], v[86:87], v[212:213]
	v_cvt_pk_bf16_f32 v88, v88, v89
	v_cvt_pk_bf16_f32 v89, v90, v91
	v_cvt_pk_bf16_f32 v90, v84, v85
	v_cvt_pk_bf16_f32 v91, v86, v87
	global_store_dwordx4 v215, v[88:91], s[94:95]
	v_mul_f32_e32 v200, 0xbfb8aa3b, v143
	v_mul_f32_e32 v202, v143, v143
	v_add_u32_e32 v215, 0x42000, v214
	v_pk_mul_f32 v[206:207], v[80:81], v[200:201] op_sel_hi:[1,0]
	v_pk_mul_f32 v[208:209], v[82:83], v[200:201] op_sel_hi:[1,0]
	v_pk_mul_f32 v[210:211], v[76:77], v[200:201] op_sel_hi:[1,0]
	v_pk_mul_f32 v[212:213], v[78:79], v[200:201] op_sel_hi:[1,0]
	v_exp_f32_e32 v206, v206
	v_exp_f32_e32 v207, v207
	v_exp_f32_e32 v208, v208
	v_exp_f32_e32 v209, v209
	v_exp_f32_e32 v210, v210
	v_exp_f32_e32 v211, v211
	v_exp_f32_e32 v212, v212
	v_exp_f32_e32 v213, v213
	v_pk_mul_f32 v[72:73], v[80:81], v[72:73]
	v_pk_mul_f32 v[74:75], v[82:83], v[74:75]
	v_pk_mul_f32 v[68:69], v[76:77], v[68:69]
	v_pk_mul_f32 v[70:71], v[78:79], v[70:71]
	v_pk_add_f32 v[206:207], v[206:207], v[204:205] op_sel_hi:[1,0]
	v_pk_add_f32 v[208:209], v[208:209], v[204:205] op_sel_hi:[1,0]
	v_pk_add_f32 v[210:211], v[210:211], v[204:205] op_sel_hi:[1,0]
	v_pk_add_f32 v[212:213], v[212:213], v[204:205] op_sel_hi:[1,0]
	v_rcp_f32_e32 v206, v206
	v_rcp_f32_e32 v207, v207
	v_rcp_f32_e32 v208, v208
	v_rcp_f32_e32 v209, v209
	v_rcp_f32_e32 v210, v210
	v_rcp_f32_e32 v211, v211
	v_rcp_f32_e32 v212, v212
	v_rcp_f32_e32 v213, v213
	v_pk_mul_f32 v[72:73], v[72:73], v[202:203] op_sel_hi:[1,0]
	v_pk_mul_f32 v[74:75], v[74:75], v[202:203] op_sel_hi:[1,0]
	v_pk_mul_f32 v[68:69], v[68:69], v[202:203] op_sel_hi:[1,0]
	v_pk_mul_f32 v[70:71], v[70:71], v[202:203] op_sel_hi:[1,0]
	v_pk_mul_f32 v[72:73], v[72:73], v[206:207]
	v_pk_mul_f32 v[74:75], v[74:75], v[208:209]
	v_pk_mul_f32 v[68:69], v[68:69], v[210:211]
	v_pk_mul_f32 v[70:71], v[70:71], v[212:213]
	v_cvt_pk_bf16_f32 v72, v72, v73
	v_cvt_pk_bf16_f32 v73, v74, v75
	v_cvt_pk_bf16_f32 v74, v68, v69
	v_cvt_pk_bf16_f32 v75, v70, v71
	global_store_dwordx4 v215, v[72:75], s[94:95]
	v_mul_f32_e32 v200, 0xbfb8aa3b, v156
	v_mul_f32_e32 v202, v156, v156
	v_add_u32_e32 v215, 0xb0000, v214
	v_pk_mul_f32 v[206:207], v[64:65], v[200:201] op_sel_hi:[1,0]
	v_pk_mul_f32 v[208:209], v[66:67], v[200:201] op_sel_hi:[1,0]
	v_pk_mul_f32 v[210:211], v[60:61], v[200:201] op_sel_hi:[1,0]
	v_pk_mul_f32 v[212:213], v[62:63], v[200:201] op_sel_hi:[1,0]
	v_exp_f32_e32 v206, v206
	v_exp_f32_e32 v207, v207
	v_exp_f32_e32 v208, v208
	v_exp_f32_e32 v209, v209
	v_exp_f32_e32 v210, v210
	v_exp_f32_e32 v211, v211
	v_exp_f32_e32 v212, v212
	v_exp_f32_e32 v213, v213
	v_pk_mul_f32 v[56:57], v[64:65], v[56:57]
	v_pk_mul_f32 v[58:59], v[66:67], v[58:59]
	v_pk_mul_f32 v[52:53], v[60:61], v[52:53]
	v_pk_mul_f32 v[54:55], v[62:63], v[54:55]
	v_pk_add_f32 v[206:207], v[206:207], v[204:205] op_sel_hi:[1,0]
	v_pk_add_f32 v[208:209], v[208:209], v[204:205] op_sel_hi:[1,0]
	v_pk_add_f32 v[210:211], v[210:211], v[204:205] op_sel_hi:[1,0]
	v_pk_add_f32 v[212:213], v[212:213], v[204:205] op_sel_hi:[1,0]
	v_rcp_f32_e32 v206, v206
	v_rcp_f32_e32 v207, v207
	v_rcp_f32_e32 v208, v208
	v_rcp_f32_e32 v209, v209
	v_rcp_f32_e32 v210, v210
	v_rcp_f32_e32 v211, v211
	v_rcp_f32_e32 v212, v212
	v_rcp_f32_e32 v213, v213
	v_pk_mul_f32 v[56:57], v[56:57], v[202:203] op_sel_hi:[1,0]
	v_pk_mul_f32 v[58:59], v[58:59], v[202:203] op_sel_hi:[1,0]
	v_pk_mul_f32 v[52:53], v[52:53], v[202:203] op_sel_hi:[1,0]
	v_pk_mul_f32 v[54:55], v[54:55], v[202:203] op_sel_hi:[1,0]
	v_pk_mul_f32 v[56:57], v[56:57], v[206:207]
	v_pk_mul_f32 v[58:59], v[58:59], v[208:209]
	v_pk_mul_f32 v[52:53], v[52:53], v[210:211]
	v_pk_mul_f32 v[54:55], v[54:55], v[212:213]
	v_cvt_pk_bf16_f32 v56, v56, v57
	v_cvt_pk_bf16_f32 v57, v58, v59
	v_cvt_pk_bf16_f32 v58, v52, v53
	v_cvt_pk_bf16_f32 v59, v54, v55
	global_store_dwordx4 v215, v[56:59], s[94:95]
	v_mul_f32_e32 v200, 0xbfb8aa3b, v157
	v_mul_f32_e32 v202, v157, v157
	v_add_u32_e32 v215, 0xc6000, v214
	v_pk_mul_f32 v[206:207], v[48:49], v[200:201] op_sel_hi:[1,0]
	v_pk_mul_f32 v[208:209], v[50:51], v[200:201] op_sel_hi:[1,0]
	v_pk_mul_f32 v[210:211], v[44:45], v[200:201] op_sel_hi:[1,0]
	v_pk_mul_f32 v[212:213], v[46:47], v[200:201] op_sel_hi:[1,0]
	v_exp_f32_e32 v206, v206
	v_exp_f32_e32 v207, v207
	v_exp_f32_e32 v208, v208
	v_exp_f32_e32 v209, v209
	v_exp_f32_e32 v210, v210
	v_exp_f32_e32 v211, v211
	v_exp_f32_e32 v212, v212
	v_exp_f32_e32 v213, v213
	v_pk_mul_f32 v[40:41], v[48:49], v[40:41]
	v_pk_mul_f32 v[42:43], v[50:51], v[42:43]
	v_pk_mul_f32 v[36:37], v[44:45], v[36:37]
	v_pk_mul_f32 v[38:39], v[46:47], v[38:39]
	v_pk_add_f32 v[206:207], v[206:207], v[204:205] op_sel_hi:[1,0]
	v_pk_add_f32 v[208:209], v[208:209], v[204:205] op_sel_hi:[1,0]
; __device__ __forceinline__ unsigned pk2(float lo, float hi) { f32x2 v = {lo, hi}; bf16x2_t b = __builtin_convertvector(v, bf16x2_t); return __builtin_bit_cast(unsigned, b); }
; __device__ __forceinline__ float silu_f(float g) { return g * __builtin_amdgcn_rcpf(1.f + __builtin_amdgcn_exp2f(g * -1.4426950408889634f)); }
; __device__ __forceinline__ void rstd_unit_start(RstdState& st, const float* ssq, int pm, int tid) {
;     if (pm != st.last_pm && tid < 256) st.pre = *(const f32x4*)(ssq + (size_t)(pm * BM + tid) * 4);
;     __device__ __forceinline__ void operator()(const f32x4 (&acc)[2][2][4][2], const Unit& u, int wr, int wc, int fr, int fq, LAS unsigned char* lds, int tid, State& st) const {
;     ...
;             for (int m = 0; m < 4; ++m) {
;                 const int row = row0 + ai * HALF + m * 16; const float r = rs[m];
;                 const f32x4 g0 = acc[ai][0][m][0] * r, g1 = acc[ai][0][m][1] * r, u0 = acc[ai][1][m][0] * r, u1 = acc[ai][1][m][1] * r;
;                 u32x4 w;
;                 w.x = pk2(silu_f(g0[0]) * u0[0], silu_f(g0[1]) * u0[1]); w.y = pk2(silu_f(g0[2]) * u0[2], silu_f(g0[3]) * u0[3]);
;                 w.z = pk2(silu_f(g1[0]) * u1[0], silu_f(g1[1]) * u1[1]); w.w = pk2(silu_f(g1[2]) * u1[2], silu_f(g1[3]) * u1[3]);
;                 *(u32x4*)(H + (size_t)row * DFF + col0) = w;
;             }
	v_pk_add_f32 v[210:211], v[210:211], v[204:205] op_sel_hi:[1,0]
	v_pk_add_f32 v[212:213], v[212:213], v[204:205] op_sel_hi:[1,0]
	v_rcp_f32_e32 v206, v206
	v_rcp_f32_e32 v207, v207
	v_rcp_f32_e32 v208, v208
	v_rcp_f32_e32 v209, v209
	v_rcp_f32_e32 v210, v210
	v_rcp_f32_e32 v211, v211
	v_rcp_f32_e32 v212, v212
	v_rcp_f32_e32 v213, v213
	v_pk_mul_f32 v[40:41], v[40:41], v[202:203] op_sel_hi:[1,0]
	v_pk_mul_f32 v[42:43], v[42:43], v[202:203] op_sel_hi:[1,0]
	v_pk_mul_f32 v[36:37], v[36:37], v[202:203] op_sel_hi:[1,0]
	v_pk_mul_f32 v[38:39], v[38:39], v[202:203] op_sel_hi:[1,0]
	v_pk_mul_f32 v[40:41], v[40:41], v[206:207]
	v_pk_mul_f32 v[42:43], v[42:43], v[208:209]
	v_pk_mul_f32 v[36:37], v[36:37], v[210:211]
	v_pk_mul_f32 v[38:39], v[38:39], v[212:213]
	v_cvt_pk_bf16_f32 v40, v40, v41
	v_cvt_pk_bf16_f32 v41, v42, v43
	v_cvt_pk_bf16_f32 v42, v36, v37
	v_cvt_pk_bf16_f32 v43, v38, v39
	global_store_dwordx4 v215, v[40:43], s[94:95]
	v_mul_f32_e32 v200, 0xbfb8aa3b, v144
	v_mul_f32_e32 v202, v144, v144
	v_add_u32_e32 v215, 0xdc000, v214
	v_pk_mul_f32 v[206:207], v[32:33], v[200:201] op_sel_hi:[1,0]
	v_pk_mul_f32 v[208:209], v[34:35], v[200:201] op_sel_hi:[1,0]
	v_pk_mul_f32 v[210:211], v[28:29], v[200:201] op_sel_hi:[1,0]
	v_pk_mul_f32 v[212:213], v[30:31], v[200:201] op_sel_hi:[1,0]
	v_exp_f32_e32 v206, v206
	v_exp_f32_e32 v207, v207
	v_exp_f32_e32 v208, v208
	v_exp_f32_e32 v209, v209
	v_exp_f32_e32 v210, v210
	v_exp_f32_e32 v211, v211
	v_exp_f32_e32 v212, v212
	v_exp_f32_e32 v213, v213
	v_pk_mul_f32 v[24:25], v[32:33], v[24:25]
	v_pk_mul_f32 v[26:27], v[34:35], v[26:27]
	v_pk_mul_f32 v[20:21], v[28:29], v[20:21]
	v_pk_mul_f32 v[22:23], v[30:31], v[22:23]
	v_pk_add_f32 v[206:207], v[206:207], v[204:205] op_sel_hi:[1,0]
	v_pk_add_f32 v[208:209], v[208:209], v[204:205] op_sel_hi:[1,0]
	v_pk_add_f32 v[210:211], v[210:211], v[204:205] op_sel_hi:[1,0]
	v_pk_add_f32 v[212:213], v[212:213], v[204:205] op_sel_hi:[1,0]
	v_rcp_f32_e32 v206, v206
	v_rcp_f32_e32 v207, v207
	v_rcp_f32_e32 v208, v208
	v_rcp_f32_e32 v209, v209
	v_rcp_f32_e32 v210, v210
	v_rcp_f32_e32 v211, v211
	v_rcp_f32_e32 v212, v212
	v_rcp_f32_e32 v213, v213
	v_pk_mul_f32 v[24:25], v[24:25], v[202:203] op_sel_hi:[1,0]
	v_pk_mul_f32 v[26:27], v[26:27], v[202:203] op_sel_hi:[1,0]
	v_pk_mul_f32 v[20:21], v[20:21], v[202:203] op_sel_hi:[1,0]
	v_pk_mul_f32 v[22:23], v[22:23], v[202:203] op_sel_hi:[1,0]
	v_pk_mul_f32 v[24:25], v[24:25], v[206:207]
	v_pk_mul_f32 v[26:27], v[26:27], v[208:209]
	v_pk_mul_f32 v[20:21], v[20:21], v[210:211]
	v_pk_mul_f32 v[22:23], v[22:23], v[212:213]
	v_cvt_pk_bf16_f32 v24, v24, v25
	v_cvt_pk_bf16_f32 v25, v26, v27
	v_cvt_pk_bf16_f32 v26, v20, v21
	v_cvt_pk_bf16_f32 v27, v22, v23
	global_store_dwordx4 v215, v[24:27], s[94:95]
	v_mul_f32_e32 v200, 0xbfb8aa3b, v145
	v_mul_f32_e32 v202, v145, v145
	v_add_u32_e32 v215, 0xf2000, v214
	v_pk_mul_f32 v[206:207], v[16:17], v[200:201] op_sel_hi:[1,0]
	v_pk_mul_f32 v[208:209], v[18:19], v[200:201] op_sel_hi:[1,0]
	v_pk_mul_f32 v[210:211], v[12:13], v[200:201] op_sel_hi:[1,0]
	v_pk_mul_f32 v[212:213], v[14:15], v[200:201] op_sel_hi:[1,0]
	v_exp_f32_e32 v206, v206
	v_exp_f32_e32 v207, v207
	v_exp_f32_e32 v208, v208
	v_exp_f32_e32 v209, v209
	v_exp_f32_e32 v210, v210
	v_exp_f32_e32 v211, v211
	v_exp_f32_e32 v212, v212
	v_exp_f32_e32 v213, v213
	v_pk_mul_f32 v[8:9], v[16:17], v[8:9]
	v_pk_mul_f32 v[10:11], v[18:19], v[10:11]
	v_pk_mul_f32 v[4:5], v[12:13], v[4:5]
	v_pk_mul_f32 v[6:7], v[14:15], v[6:7]
	v_pk_add_f32 v[206:207], v[206:207], v[204:205] op_sel_hi:[1,0]
	v_pk_add_f32 v[208:209], v[208:209], v[204:205] op_sel_hi:[1,0]
	v_pk_add_f32 v[210:211], v[210:211], v[204:205] op_sel_hi:[1,0]
	v_pk_add_f32 v[212:213], v[212:213], v[204:205] op_sel_hi:[1,0]
	v_rcp_f32_e32 v206, v206
	v_rcp_f32_e32 v207, v207
	v_rcp_f32_e32 v208, v208
	v_rcp_f32_e32 v209, v209
	v_rcp_f32_e32 v210, v210
	v_rcp_f32_e32 v211, v211
	v_rcp_f32_e32 v212, v212
	v_rcp_f32_e32 v213, v213
	v_pk_mul_f32 v[8:9], v[8:9], v[202:203] op_sel_hi:[1,0]
	v_pk_mul_f32 v[10:11], v[10:11], v[202:203] op_sel_hi:[1,0]
	v_pk_mul_f32 v[4:5], v[4:5], v[202:203] op_sel_hi:[1,0]
	v_pk_mul_f32 v[6:7], v[6:7], v[202:203] op_sel_hi:[1,0]
	v_pk_mul_f32 v[8:9], v[8:9], v[206:207]
	v_pk_mul_f32 v[10:11], v[10:11], v[208:209]
	v_pk_mul_f32 v[4:5], v[4:5], v[210:211]
	v_pk_mul_f32 v[6:7], v[6:7], v[212:213]
	v_cvt_pk_bf16_f32 v8, v8, v9
	v_cvt_pk_bf16_f32 v9, v10, v11
	v_cvt_pk_bf16_f32 v10, v4, v5
	v_cvt_pk_bf16_f32 v11, v6, v7
	global_store_dwordx4 v215, v[8:11], s[94:95]
	s_mov_b64 s[6:7], -1
	s_cbranch_vccnz .LBB0_713
	s_cmp_lg_u32 s22, s9
	s_cselect_b64 s[6:7], -1, 0
	s_and_b64 s[14:15], s[38:39], s[6:7]
	s_and_saveexec_b64 s[6:7], s[14:15]
	s_cbranch_execz .LBB0_728
	s_nop 0
	v_lshl_add_u32 v0, s22, 8, v146
	v_ashrrev_i32_e32 v1, 31, v0
	v_lshl_add_u64 v[0:1], v[0:1], 4, s[88:89]
	global_load_dwordx4 v[0:3], v[0:1], off
